# MODE1 epilogue row loops: next iteration's two LDS tile reads prefetched into spare registers (per-use LDS waits removed)
# baseline (speedup 1.0000x reference)
.LBB0_286:
	v_add_u32_e32 v129, 0x400, v144
	v_add_u32_e32 v132, 0x800, v144
	v_add_u32_e32 v133, 0xc00, v144
	ds_write2_b32 v144, v104, v108 offset1:16
	ds_write2_b32 v129, v105, v109 offset0:4 offset1:20
	ds_write2_b32 v132, v106, v110 offset0:8 offset1:24
	ds_write2_b32 v133, v107, v111 offset0:12 offset1:28
	ds_write2_b32 v144, v120, v124 offset0:128 offset1:144
	ds_write2_b32 v129, v121, v125 offset0:132 offset1:148
	ds_write2_b32 v132, v122, v126 offset0:136 offset1:152
	ds_write2_b32 v133, v123, v127 offset0:140 offset1:156
	v_add_u32_e32 v120, 0x4000, v144
	v_add_u32_e32 v121, 0x4400, v144
	v_add_u32_e32 v122, 0x4800, v144
	v_add_u32_e32 v123, 0x4c00, v144
	ds_write2_b32 v120, v96, v100 offset0:64 offset1:80
	ds_write2_b32 v121, v97, v101 offset0:68 offset1:84
	ds_write2_b32 v122, v98, v102 offset0:72 offset1:88
	ds_write2_b32 v123, v99, v103 offset0:76 offset1:92
	ds_write2_b32 v120, v112, v116 offset0:192 offset1:208
	ds_write2_b32 v121, v113, v117 offset0:196 offset1:212
	ds_write2_b32 v122, v114, v118 offset0:200 offset1:216
	ds_write2_b32 v123, v115, v119 offset0:204 offset1:220
	v_mov_b32_e32 v116, v224
	s_waitcnt vmcnt(0) lgkmcnt(0)
	s_barrier
	s_cmp_gt_i32 s18, 63
	v_lshlrev_b32_e32 v96, 3, v116
	v_and_b32_e32 v97, 0xe0, v96
	v_lshlrev_b32_e32 v96, 2, v116
	v_and_b32_e32 v100, 12, v96
	v_or_b32_e32 v98, v97, v100
	v_or_b32_e32 v96, s16, v98
	v_and_b32_e32 v99, 4, v116
	v_cmp_eq_u32_e64 s[4:5], 0, v99
	v_lshlrev_b32_e32 v98, 2, v98
	v_mov_b32_e32 v99, v131
	v_cmp_eq_u32_e64 s[6:7], 0, v97
	v_ashrrev_i32_e32 v97, 31, v96
	v_lshl_add_u64 v[104:105], s[74:75], 0, v[98:99]
	v_lshlrev_b64 v[98:99], 1, v[96:97]
	v_lshl_add_u64 v[106:107], s[72:73], 0, v[98:99]
	v_lshl_add_u64 v[108:109], s[28:29], 0, v[98:99]
	v_cvt_f32_ubyte0_e32 v98, v100
	v_mul_f32_e32 v98, 0xbf549a78, v98
	v_exp_f32_e32 v118, v98
	v_or_b32_e32 v98, 1, v100
	v_cvt_f32_ubyte0_e32 v98, v98
	v_mul_f32_e32 v98, 0xbf549a78, v98
	v_exp_f32_e32 v119, v98
	v_or_b32_e32 v98, 2, v100
	v_cvt_f32_ubyte0_e32 v98, v98
	v_mul_f32_e32 v98, 0xbf549a78, v98
	v_readlane_b32 s48, v255, 38
	s_cselect_b64 s[12:13], -1, 0
	s_and_b32 s0, 0xffff, s45
	v_exp_f32_e32 v124, v98
	v_or_b32_e32 v98, 3, v100
	v_readlane_b32 s54, v255, 44
	v_readlane_b32 s55, v255, 45
	s_cmp_gt_u32 s0, 11
	v_cvt_f32_ubyte0_e32 v98, v98
	v_lshl_add_u64 v[110:111], v[96:97], 2, s[54:55]
	v_lshlrev_b32_e32 v96, 5, v116
	s_cselect_b64 s[24:25], -1, 0
	s_cmp_gt_u32 s0, 27
	v_ashrrev_i32_e32 v117, 5, v116
	v_mul_f32_e32 v98, 0xbf549a78, v98
	v_and_b32_e32 v96, 0x380, v96
	s_cselect_b64 s[20:21], -1, 0
	s_cmp_gt_i32 s18, 31
	v_exp_f32_e32 v125, v98
	v_mad_u64_u32 v[96:97], s[0:1], v117, s60, v[96:97]
	s_cselect_b64 s[22:23], -1, 0
	s_cmpk_lt_i32 s38, 0x1000
	v_and_b32_e32 v97, 3, v116
	s_cselect_b64 s[8:9], -1, 0
	s_cmpk_gt_i32 s38, 0xfff
	v_lshlrev_b32_e32 v97, 4, v97
	s_cselect_b64 s[10:11], -1, 0
	s_mov_b32 s15, 0
	s_and_b64 s[18:19], s[22:23], s[8:9]
	v_add3_u32 v126, v96, v97, 16
	v_lshlrev_b32_e32 v127, 1, v117
	v_readlane_b32 s49, v255, 39
	v_readlane_b32 s50, v255, 40
	v_readlane_b32 s51, v255, 41
	v_readlane_b32 s52, v255, 42
	v_readlane_b32 s53, v255, 43
	v_add_u32_e32 v178, s15, v126
	ds_read_b128 v[170:173], v178
	ds_read_b128 v[174:177], v178 offset:64
	s_branch .LBB0_288

.LBB0_288:
	v_and_b32_e32 v114, 31, v117
	v_and_b32_e32 v96, 0xffffffc0, v127
	v_or_b32_e32 v97, s38, v114
	v_add_u32_e32 v100, s15, v126
	v_add_u32_e32 v112, v97, v96
	s_waitcnt lgkmcnt(0)
	v_mov_b32_e32 v96, v170
	v_mov_b32_e32 v97, v171
	v_mov_b32_e32 v98, v172
	v_mov_b32_e32 v99, v173
	v_mov_b32_e32 v100, v174
	v_mov_b32_e32 v101, v175
	v_mov_b32_e32 v102, v176
	v_mov_b32_e32 v103, v177
	v_add_u32_e32 v178, s15, v126
	v_add_u32_e32 v178, 0x4100, v178
	ds_read_b128 v[170:173], v178
	ds_read_b128 v[174:177], v178 offset:64
	s_mov_b64 s[0:1], -1
	s_and_b64 vcc, exec, s[12:13]
	s_cbranch_vccz .LBB0_301
	s_and_b64 vcc, exec, s[24:25]
	s_cbranch_vccz .LBB0_297
	s_and_b64 vcc, exec, s[20:21]
	s_cbranch_vccz .LBB0_294
	s_and_saveexec_b64 s[0:1], s[6:7]
	s_cbranch_execz .LBB0_293
	v_ashrrev_i32_e32 v113, 31, v112
	v_lshlrev_b64 v[134:135], 7, v[112:113]
	v_lshl_add_u64 v[134:135], v[104:105], 0, v[134:135]
	global_store_dwordx4 v[134:135], v[96:99], off
	global_store_dwordx4 v[134:135], v[100:103], off offset:64

.LBB0_294:
	s_andn2_b64 vcc, exec, s[0:1]
	s_cbranch_vccnz .LBB0_296
	v_cvt_pk_bf16_f32 v135, v98, v99
	v_cvt_pk_bf16_f32 v134, v96, v97
	v_mad_i64_i32 v[136:137], s[0:1], v112, s66, v[106:107]
	global_store_dwordx2 v[136:137], v[134:135], off
	v_cvt_pk_bf16_f32 v135, v102, v103
	v_cvt_pk_bf16_f32 v134, v100, v101
	global_store_dwordx2 v[136:137], v[134:135], off offset:32

.LBB0_297:
	s_andn2_b64 vcc, exec, s[0:1]
	s_cbranch_vccnz .LBB0_300
	s_andn2_b64 vcc, exec, s[8:9]
	s_cbranch_vccnz .LBB0_300
	v_ashrrev_i32_e32 v113, 31, v112
	v_lshlrev_b64 v[134:135], 12, v[112:113]
	v_lshl_add_u64 v[134:135], v[110:111], 0, v[134:135]
	v_add_co_u32_e32 v134, vcc, 0x4ffe000, v134
	s_nop 1
	v_addc_co_u32_e32 v135, vcc, 0, v135, vcc
	global_store_dwordx4 v[134:135], v[96:99], off
	global_store_dwordx4 v[134:135], v[100:103], off offset:64

.LBB0_301:
	s_andn2_b64 vcc, exec, s[0:1]
	s_cbranch_vccnz .LBB0_287
	s_andn2_b64 vcc, exec, s[18:19]
	s_cbranch_vccnz .LBB0_308
	v_ashrrev_i32_e32 v113, 31, v112
	v_lshlrev_b64 v[134:135], 12, v[112:113]
	v_lshl_add_u64 v[134:135], v[110:111], 0, v[134:135]
	v_add_co_u32_e32 v134, vcc, 0x3fff000, v134
	s_nop 1
	v_addc_co_u32_e32 v135, vcc, 0, v135, vcc
	global_store_dwordx4 v[134:135], v[96:99], off
	global_store_dwordx4 v[134:135], v[100:103], off offset:64
	v_cndmask_b32_e64 v113, 0, 1, s[10:11]
	v_cmp_ne_u32_e64 s[0:1], 1, v113
	s_andn2_b64 vcc, exec, s[10:11]
	s_cbranch_vccz .LBB0_309

.LBB0_307:
	v_ashrrev_i32_e32 v115, 31, v114
	v_lshlrev_b64 v[114:115], 11, v[114:115]
	v_lshl_add_u64 v[114:115], v[108:109], 0, v[114:115]
	v_add_co_u32_e32 v114, vcc, 0xfaff000, v114
	v_cvt_pk_bf16_f32 v135, v98, v99
	v_cvt_pk_bf16_f32 v134, v96, v97
	v_addc_co_u32_e32 v115, vcc, 0, v115, vcc
	global_store_dwordx2 v[114:115], v[134:135], off offset:2048
	v_cvt_pk_bf16_f32 v135, v102, v103
	v_cvt_pk_bf16_f32 v134, v100, v101
	global_store_dwordx2 v[114:115], v[134:135], off offset:2080
	s_branch .LBB0_287

.LBB0_309:
	v_bfe_u32 v113, v112, 6, 4
	v_cndmask_b32_e64 v113, v114, v113, s[4:5]
	v_cvt_f32_ubyte0_e32 v113, v113
	v_mul_f32_e32 v114, v118, v113
	v_mul_f32_e32 v115, 0.15915494, v114
	v_sin_f32_e32 v114, v115
	v_cos_f32_e32 v134, v115
	v_mul_f32_e32 v115, v119, v113
	v_mul_f32_e32 v135, 0.15915494, v115
	v_mul_f32_e32 v136, v124, v113
	v_mul_f32_e32 v113, v125, v113
	v_sin_f32_e32 v115, v135
	v_mul_f32_e32 v136, 0.15915494, v136
	v_mul_f32_e32 v113, 0.15915494, v113
	v_cos_f32_e32 v135, v135
	v_cos_f32_e32 v139, v136
	v_sin_f32_e32 v141, v136
	v_sin_f32_e32 v143, v113
	v_cos_f32_e32 v142, v113
	v_pk_mul_f32 v[136:137], v[100:101], v[114:115]
	v_pk_mul_f32 v[100:101], v[100:101], v[134:135]
	v_mul_f32_e32 v140, v102, v141
	v_mul_f32_e32 v168, v102, v139
	v_mov_b32_e32 v102, v99
	v_pk_fma_f32 v[134:135], v[96:97], v[134:135], v[136:137] neg_lo:[0,0,1] neg_hi:[0,0,1]
	v_mov_b32_e32 v136, v143
	v_mov_b32_e32 v137, v142
	v_mul_f32_e32 v138, v98, v139
	v_mul_f32_e32 v166, v98, v141
	v_pk_mul_f32 v[98:99], v[102:103], v[142:143]
	v_pk_mul_f32 v[102:103], v[102:103], v[136:137]
	v_mov_b32_e32 v139, v98
	v_mov_b32_e32 v141, v99
	v_mov_b32_e32 v167, v102
	v_mov_b32_e32 v169, v103
	v_pk_add_f32 v[98:99], v[138:139], v[140:141] neg_lo:[0,1] neg_hi:[0,1]
	v_pk_fma_f32 v[100:101], v[96:97], v[114:115], v[100:101]
	v_pk_add_f32 v[102:103], v[166:167], v[168:169]
	v_mov_b32_e32 v96, v134
	v_mov_b32_e32 v97, v135
	s_mov_b64 s[26:27], -1
	s_and_b64 vcc, exec, s[22:23]
	s_cbranch_vccnz .LBB0_305
.LBB0_310:
	s_and_b64 vcc, exec, s[26:27]
	s_cbranch_vccz .LBB0_287
	v_cvt_pk_bf16_f32 v99, v98, v99
	v_cvt_pk_bf16_f32 v98, v96, v97
	v_mad_i64_i32 v[96:97], s[0:1], v112, s66, v[106:107]
	global_store_dwordx2 v[96:97], v[98:99], off
	v_cvt_pk_bf16_f32 v99, v102, v103
	v_cvt_pk_bf16_f32 v98, v100, v101
	global_store_dwordx2 v[96:97], v[98:99], off offset:32
	s_branch .LBB0_287

.LBB0_315:
	s_waitcnt lgkmcnt(0)
	s_barrier
	ds_write2_b32 v144, v72, v76 offset1:16
	ds_write2_b32 v129, v73, v77 offset0:4 offset1:20
	ds_write2_b32 v132, v74, v78 offset0:8 offset1:24
	ds_write2_b32 v133, v75, v79 offset0:12 offset1:28
	ds_write2_b32 v144, v88, v92 offset0:128 offset1:144
	ds_write2_b32 v129, v89, v93 offset0:132 offset1:148
	ds_write2_b32 v132, v90, v94 offset0:136 offset1:152
	ds_write2_b32 v133, v91, v95 offset0:140 offset1:156
	ds_write2_b32 v120, v64, v68 offset0:64 offset1:80
	ds_write2_b32 v121, v65, v69 offset0:68 offset1:84
	ds_write2_b32 v122, v66, v70 offset0:72 offset1:88
	ds_write2_b32 v123, v67, v71 offset0:76 offset1:92
	ds_write2_b32 v120, v80, v84 offset0:192 offset1:208
	ds_write2_b32 v121, v81, v85 offset0:196 offset1:212
	ds_write2_b32 v122, v82, v86 offset0:200 offset1:216
	ds_write2_b32 v123, v83, v87 offset0:204 offset1:220
	v_mov_b32_e32 v84, v224
	s_waitcnt lgkmcnt(0)
	s_barrier
	v_readlane_b32 s44, v255, 38
	v_lshlrev_b32_e32 v64, 3, v84
	v_and_b32_e32 v65, 0xe0, v64
	v_lshlrev_b32_e32 v64, 2, v84
	v_and_b32_e32 v68, 12, v64
	v_or_b32_e32 v66, v65, v68
	v_or_b32_e32 v64, s16, v66
	v_and_b32_e32 v67, 4, v84
	v_cmp_eq_u32_e64 s[8:9], 0, v67
	v_lshlrev_b32_e32 v66, 2, v66
	v_mov_b32_e32 v67, v131
	v_cmp_eq_u32_e64 s[10:11], 0, v65
	v_ashrrev_i32_e32 v65, 31, v64
	v_lshl_add_u64 v[72:73], s[74:75], 0, v[66:67]
	v_lshlrev_b64 v[66:67], 1, v[64:65]
	v_lshl_add_u64 v[74:75], s[72:73], 0, v[66:67]
	v_lshl_add_u64 v[76:77], s[28:29], 0, v[66:67]
	v_cvt_f32_ubyte0_e32 v66, v68
	v_mul_f32_e32 v66, 0xbf549a78, v66
	v_exp_f32_e32 v86, v66
	v_or_b32_e32 v66, 1, v68
	v_cvt_f32_ubyte0_e32 v66, v66
	v_mul_f32_e32 v66, 0xbf549a78, v66
	v_exp_f32_e32 v87, v66
	v_or_b32_e32 v66, 2, v68
	v_cvt_f32_ubyte0_e32 v66, v66
	v_mul_f32_e32 v66, 0xbf549a78, v66
	v_exp_f32_e32 v88, v66
	v_or_b32_e32 v66, 3, v68
	v_readlane_b32 s50, v255, 44
	v_readlane_b32 s51, v255, 45
	v_cvt_f32_ubyte0_e32 v66, v66
	v_ashrrev_i32_e32 v85, 5, v84
	v_lshl_add_u64 v[78:79], v[64:65], 2, s[50:51]
	v_lshlrev_b32_e32 v64, 5, v84
	v_mul_f32_e32 v66, 0xbf549a78, v66
	v_and_b32_e32 v64, 0x380, v64
	s_or_b32 s15, s38, 32
	v_exp_f32_e32 v89, v66
	v_mad_u64_u32 v[64:65], s[0:1], v85, s60, v[64:65]
	s_cmpk_lt_i32 s38, 0xfe0
	v_and_b32_e32 v65, 3, v84
	s_cselect_b64 s[18:19], -1, 0
	s_cmpk_gt_i32 s38, 0xfdf
	v_lshlrev_b32_e32 v65, 4, v65
	s_cselect_b64 s[52:53], -1, 0
	s_mov_b32 s17, 0
	s_and_b64 s[54:55], s[22:23], s[18:19]
	v_add3_u32 v90, v64, v65, 16
	v_lshlrev_b32_e32 v91, 1, v85
	v_readlane_b32 s45, v255, 39
	v_readlane_b32 s46, v255, 40
	v_readlane_b32 s47, v255, 41
	v_readlane_b32 s48, v255, 42
	v_readlane_b32 s49, v255, 43
	v_add_u32_e32 v178, s17, v90
	ds_read_b128 v[170:173], v178
	ds_read_b128 v[174:177], v178 offset:64
	s_branch .LBB0_317

.LBB0_317:
	v_and_b32_e32 v64, 0xffffffc0, v91
	v_and_or_b32 v82, v85, 31, s15
	v_add_u32_e32 v68, s17, v90
	v_add_u32_e32 v80, v82, v64
	s_waitcnt lgkmcnt(0)
	v_mov_b32_e32 v64, v170
	v_mov_b32_e32 v65, v171
	v_mov_b32_e32 v66, v172
	v_mov_b32_e32 v67, v173
	v_mov_b32_e32 v68, v174
	v_mov_b32_e32 v69, v175
	v_mov_b32_e32 v70, v176
	v_mov_b32_e32 v71, v177
	v_add_u32_e32 v178, s17, v90
	v_add_u32_e32 v178, 0x4100, v178
	ds_read_b128 v[170:173], v178
	ds_read_b128 v[174:177], v178 offset:64
	v_cndmask_b32_e64 v81, 0, 1, s[12:13]
	v_cmp_ne_u32_e64 s[4:5], 1, v81
	v_cndmask_b32_e64 v81, 0, 1, s[24:25]
	s_mov_b64 s[0:1], -1
	s_andn2_b64 vcc, exec, s[12:13]
	v_cmp_ne_u32_e64 s[6:7], 1, v81
	s_cbranch_vccnz .LBB0_330
	s_and_b64 vcc, exec, s[6:7]
	s_cbranch_vccnz .LBB0_326
	s_andn2_b64 vcc, exec, s[20:21]
	s_cbranch_vccnz .LBB0_323
	s_and_saveexec_b64 s[0:1], s[10:11]
	s_cbranch_execz .LBB0_322
	v_ashrrev_i32_e32 v81, 31, v80
	v_lshlrev_b64 v[92:93], 7, v[80:81]
	v_lshl_add_u64 v[92:93], v[72:73], 0, v[92:93]
	global_store_dwordx4 v[92:93], v[64:67], off
	global_store_dwordx4 v[92:93], v[68:71], off offset:64

.LBB0_323:
	s_andn2_b64 vcc, exec, s[0:1]
	s_cbranch_vccnz .LBB0_325
	v_cvt_pk_bf16_f32 v93, v66, v67
	v_cvt_pk_bf16_f32 v92, v64, v65
	v_mad_i64_i32 v[94:95], s[0:1], v80, s66, v[74:75]
	global_store_dwordx2 v[94:95], v[92:93], off
	v_cvt_pk_bf16_f32 v93, v70, v71
	v_cvt_pk_bf16_f32 v92, v68, v69
	global_store_dwordx2 v[94:95], v[92:93], off offset:32

.LBB0_326:
	s_andn2_b64 vcc, exec, s[0:1]
	s_cbranch_vccnz .LBB0_329
	s_andn2_b64 vcc, exec, s[18:19]
	s_cbranch_vccnz .LBB0_329
	v_ashrrev_i32_e32 v81, 31, v80
	v_lshlrev_b64 v[92:93], 12, v[80:81]
	v_lshl_add_u64 v[92:93], v[78:79], 0, v[92:93]
	v_add_co_u32_e32 v92, vcc, 0x4ffe000, v92
	s_nop 1
	v_addc_co_u32_e32 v93, vcc, 0, v93, vcc
	global_store_dwordx4 v[92:93], v[64:67], off
	global_store_dwordx4 v[92:93], v[68:71], off offset:64

.LBB0_330:
	s_andn2_b64 vcc, exec, s[0:1]
	s_cbranch_vccnz .LBB0_316
	s_andn2_b64 vcc, exec, s[54:55]
	s_cbranch_vccnz .LBB0_337
	v_ashrrev_i32_e32 v81, 31, v80
	v_lshlrev_b64 v[92:93], 12, v[80:81]
	v_lshl_add_u64 v[92:93], v[78:79], 0, v[92:93]
	v_add_co_u32_e32 v92, vcc, 0x3fff000, v92
	s_nop 1
	v_addc_co_u32_e32 v93, vcc, 0, v93, vcc
	global_store_dwordx4 v[92:93], v[64:67], off
	global_store_dwordx4 v[92:93], v[68:71], off offset:64
	v_cndmask_b32_e64 v81, 0, 1, s[52:53]
	v_cmp_ne_u32_e64 s[0:1], 1, v81
	s_andn2_b64 vcc, exec, s[52:53]
	s_cbranch_vccz .LBB0_338

.LBB0_336:
	v_ashrrev_i32_e32 v83, 31, v82
	v_lshlrev_b64 v[82:83], 11, v[82:83]
	v_lshl_add_u64 v[82:83], v[76:77], 0, v[82:83]
	v_add_co_u32_e32 v82, vcc, 0xfaff000, v82
	v_cvt_pk_bf16_f32 v93, v66, v67
	v_cvt_pk_bf16_f32 v92, v64, v65
	v_addc_co_u32_e32 v83, vcc, 0, v83, vcc
	global_store_dwordx2 v[82:83], v[92:93], off offset:2048
	v_cvt_pk_bf16_f32 v93, v70, v71
	v_cvt_pk_bf16_f32 v92, v68, v69
	global_store_dwordx2 v[82:83], v[92:93], off offset:2080
	s_branch .LBB0_316

.LBB0_338:
	v_and_b32_e32 v81, 63, v82
	v_bfe_u32 v82, v80, 6, 4
	v_cndmask_b32_e64 v81, v81, v82, s[8:9]
	v_cvt_f32_ubyte0_e32 v81, v81
	v_mul_f32_e32 v82, v86, v81
	v_mul_f32_e32 v83, 0.15915494, v82
	v_sin_f32_e32 v82, v83
	v_cos_f32_e32 v92, v83
	v_mul_f32_e32 v83, v87, v81
	v_mul_f32_e32 v93, 0.15915494, v83
	v_mul_f32_e32 v94, v88, v81
	v_mul_f32_e32 v81, v89, v81
	v_sin_f32_e32 v83, v93
	v_mul_f32_e32 v94, 0.15915494, v94
	v_mul_f32_e32 v81, 0.15915494, v81
	v_cos_f32_e32 v93, v93
	v_cos_f32_e32 v97, v94
	v_sin_f32_e32 v99, v94
	v_sin_f32_e32 v101, v81
	v_cos_f32_e32 v100, v81
	v_pk_mul_f32 v[94:95], v[68:69], v[82:83]
	v_pk_mul_f32 v[68:69], v[68:69], v[92:93]
	v_mul_f32_e32 v98, v70, v99
	v_mul_f32_e32 v104, v70, v97
	v_mov_b32_e32 v70, v67
	v_pk_fma_f32 v[92:93], v[64:65], v[92:93], v[94:95] neg_lo:[0,0,1] neg_hi:[0,0,1]
	v_mov_b32_e32 v94, v101
	v_mov_b32_e32 v95, v100
	v_mul_f32_e32 v96, v66, v97
	v_mul_f32_e32 v102, v66, v99
	v_pk_mul_f32 v[66:67], v[70:71], v[100:101]
	v_pk_mul_f32 v[70:71], v[70:71], v[94:95]
	v_mov_b32_e32 v97, v66
	v_mov_b32_e32 v99, v67
	v_mov_b32_e32 v103, v70
	v_mov_b32_e32 v105, v71
	v_pk_add_f32 v[66:67], v[96:97], v[98:99] neg_lo:[0,1] neg_hi:[0,1]
	v_pk_fma_f32 v[68:69], v[64:65], v[82:83], v[68:69]
	v_pk_add_f32 v[70:71], v[102:103], v[104:105]
	v_mov_b32_e32 v64, v92
	v_mov_b32_e32 v65, v93
	s_andn2_b64 vcc, exec, s[22:23]
	s_mov_b64 s[56:57], -1
	s_cbranch_vccz .LBB0_334
.LBB0_339:
	s_and_b64 vcc, exec, s[56:57]
	s_cbranch_vccz .LBB0_316
	v_cvt_pk_bf16_f32 v67, v66, v67
	v_cvt_pk_bf16_f32 v66, v64, v65
	v_mad_i64_i32 v[64:65], s[0:1], v80, s66, v[74:75]
	global_store_dwordx2 v[64:65], v[66:67], off
	v_cvt_pk_bf16_f32 v67, v70, v71
	v_cvt_pk_bf16_f32 v66, v68, v69
	global_store_dwordx2 v[64:65], v[66:67], off offset:32
	s_branch .LBB0_316

.LBB0_344:
	s_waitcnt lgkmcnt(0)
	s_barrier
	ds_write2_b32 v144, v40, v44 offset1:16
	ds_write2_b32 v129, v41, v45 offset0:4 offset1:20
	ds_write2_b32 v132, v42, v46 offset0:8 offset1:24
	ds_write2_b32 v133, v43, v47 offset0:12 offset1:28
	ds_write2_b32 v144, v56, v60 offset0:128 offset1:144
	ds_write2_b32 v129, v57, v61 offset0:132 offset1:148
	ds_write2_b32 v132, v58, v62 offset0:136 offset1:152
	ds_write2_b32 v133, v59, v63 offset0:140 offset1:156
	ds_write2_b32 v120, v32, v36 offset0:64 offset1:80
	ds_write2_b32 v121, v33, v37 offset0:68 offset1:84
	ds_write2_b32 v122, v34, v38 offset0:72 offset1:88
	ds_write2_b32 v123, v35, v39 offset0:76 offset1:92
	ds_write2_b32 v120, v48, v52 offset0:192 offset1:208
	ds_write2_b32 v121, v49, v53 offset0:196 offset1:212
	ds_write2_b32 v122, v50, v54 offset0:200 offset1:216
	ds_write2_b32 v123, v51, v55 offset0:204 offset1:220
	v_mov_b32_e32 v52, v224
	s_waitcnt lgkmcnt(0)
	s_barrier
	v_readlane_b32 s44, v255, 38
	v_lshlrev_b32_e32 v32, 3, v52
	v_and_b32_e32 v33, 0xe0, v32
	v_lshlrev_b32_e32 v32, 2, v52
	v_and_b32_e32 v36, 12, v32
	v_or_b32_e32 v34, v33, v36
	v_or_b32_e32 v32, s16, v34
	v_and_b32_e32 v35, 4, v52
	v_cmp_eq_u32_e64 s[10:11], 0, v35
	v_lshlrev_b32_e32 v34, 2, v34
	v_mov_b32_e32 v35, v131
	v_cmp_eq_u32_e64 s[12:13], 0, v33
	v_ashrrev_i32_e32 v33, 31, v32
	v_lshl_add_u64 v[40:41], s[74:75], 0, v[34:35]
	v_lshlrev_b64 v[34:35], 1, v[32:33]
	v_lshl_add_u64 v[42:43], s[72:73], 0, v[34:35]
	v_lshl_add_u64 v[44:45], s[28:29], 0, v[34:35]
	v_cvt_f32_ubyte0_e32 v34, v36
	v_mul_f32_e32 v34, 0xbf549a78, v34
	v_exp_f32_e32 v54, v34
	v_or_b32_e32 v34, 1, v36
	v_cvt_f32_ubyte0_e32 v34, v34
	v_mul_f32_e32 v34, 0xbf549a78, v34
	v_exp_f32_e32 v55, v34
	v_or_b32_e32 v34, 2, v36
	v_cvt_f32_ubyte0_e32 v34, v34
	v_mul_f32_e32 v34, 0xbf549a78, v34
	v_exp_f32_e32 v56, v34
	v_or_b32_e32 v34, 3, v36
	v_readlane_b32 s50, v255, 44
	v_readlane_b32 s51, v255, 45
	v_cvt_f32_ubyte0_e32 v34, v34
	v_ashrrev_i32_e32 v53, 5, v52
	v_lshl_add_u64 v[46:47], v[32:33], 2, s[50:51]
	v_lshlrev_b32_e32 v32, 5, v52
	v_mul_f32_e32 v34, 0xbf549a78, v34
	v_and_b32_e32 v32, 0x380, v32
	v_exp_f32_e32 v57, v34
	v_mad_u64_u32 v[32:33], s[0:1], v53, s60, v[32:33]
	s_cmpk_lt_i32 s38, 0xf80
	v_and_b32_e32 v33, 3, v52
	s_cselect_b64 s[24:25], -1, 0
	s_cmpk_gt_i32 s38, 0xf7f
	v_lshlrev_b32_e32 v33, 4, v33
	s_cselect_b64 s[18:19], -1, 0
	s_mov_b32 s15, 0
	s_and_b64 s[26:27], s[22:23], s[24:25]
	v_add3_u32 v58, v32, v33, 16
	v_lshlrev_b32_e32 v59, 1, v53
	v_readlane_b32 s45, v255, 39
	v_readlane_b32 s46, v255, 40
	v_readlane_b32 s47, v255, 41
	v_readlane_b32 s48, v255, 42
	v_readlane_b32 s49, v255, 43
	v_add_u32_e32 v178, s15, v58
	ds_read_b128 v[170:173], v178
	ds_read_b128 v[174:177], v178 offset:64
	s_branch .LBB0_346

.LBB0_346:
	v_and_b32_e32 v50, 31, v53
	v_and_b32_e32 v32, 0xffffffc0, v59
	v_or_b32_e32 v33, s14, v50
	v_add_u32_e32 v36, s15, v58
	v_add_u32_e32 v48, v33, v32
	s_waitcnt lgkmcnt(0)
	v_mov_b32_e32 v32, v170
	v_mov_b32_e32 v33, v171
	v_mov_b32_e32 v34, v172
	v_mov_b32_e32 v35, v173
	v_mov_b32_e32 v36, v174
	v_mov_b32_e32 v37, v175
	v_mov_b32_e32 v38, v176
	v_mov_b32_e32 v39, v177
	v_add_u32_e32 v178, s15, v58
	v_add_u32_e32 v178, 0x4100, v178
	ds_read_b128 v[170:173], v178
	ds_read_b128 v[174:177], v178 offset:64
	s_mov_b64 s[0:1], -1
	s_and_b64 vcc, exec, s[4:5]
	s_cbranch_vccnz .LBB0_359
	s_and_b64 vcc, exec, s[6:7]
	s_cbranch_vccnz .LBB0_355
	s_andn2_b64 vcc, exec, s[20:21]
	s_cbranch_vccnz .LBB0_352
	s_and_saveexec_b64 s[0:1], s[12:13]
	s_cbranch_execz .LBB0_351
	v_ashrrev_i32_e32 v49, 31, v48
	v_lshlrev_b64 v[60:61], 7, v[48:49]
	v_lshl_add_u64 v[60:61], v[40:41], 0, v[60:61]
	global_store_dwordx4 v[60:61], v[32:35], off
	global_store_dwordx4 v[60:61], v[36:39], off offset:64

.LBB0_352:
	s_andn2_b64 vcc, exec, s[0:1]
	s_cbranch_vccnz .LBB0_354
	v_cvt_pk_bf16_f32 v61, v34, v35
	v_cvt_pk_bf16_f32 v60, v32, v33
	v_mad_i64_i32 v[62:63], s[0:1], v48, s66, v[42:43]
	global_store_dwordx2 v[62:63], v[60:61], off
	v_cvt_pk_bf16_f32 v61, v38, v39
	v_cvt_pk_bf16_f32 v60, v36, v37
	global_store_dwordx2 v[62:63], v[60:61], off offset:32

.LBB0_355:
	s_andn2_b64 vcc, exec, s[0:1]
	s_cbranch_vccnz .LBB0_358
	s_andn2_b64 vcc, exec, s[24:25]
	s_cbranch_vccnz .LBB0_358
	v_ashrrev_i32_e32 v49, 31, v48
	v_lshlrev_b64 v[60:61], 12, v[48:49]
	v_lshl_add_u64 v[60:61], v[46:47], 0, v[60:61]
	v_add_co_u32_e32 v60, vcc, 0x4ffe000, v60
	s_nop 1
	v_addc_co_u32_e32 v61, vcc, 0, v61, vcc
	global_store_dwordx4 v[60:61], v[32:35], off
	global_store_dwordx4 v[60:61], v[36:39], off offset:64

.LBB0_359:
	s_andn2_b64 vcc, exec, s[0:1]
	s_cbranch_vccnz .LBB0_345
	s_andn2_b64 vcc, exec, s[26:27]
	s_cbranch_vccnz .LBB0_366
	v_ashrrev_i32_e32 v49, 31, v48
	v_lshlrev_b64 v[60:61], 12, v[48:49]
	v_lshl_add_u64 v[60:61], v[46:47], 0, v[60:61]
	v_add_co_u32_e32 v60, vcc, 0x3fff000, v60
	s_nop 1
	v_addc_co_u32_e32 v61, vcc, 0, v61, vcc
	global_store_dwordx4 v[60:61], v[32:35], off
	global_store_dwordx4 v[60:61], v[36:39], off offset:64
	v_cndmask_b32_e64 v49, 0, 1, s[18:19]
	v_cmp_ne_u32_e64 s[0:1], 1, v49
	s_andn2_b64 vcc, exec, s[18:19]
	s_cbranch_vccz .LBB0_367

.LBB0_365:
	v_ashrrev_i32_e32 v51, 31, v50
	v_lshlrev_b64 v[50:51], 11, v[50:51]
	v_lshl_add_u64 v[50:51], v[44:45], 0, v[50:51]
	v_add_co_u32_e32 v50, vcc, 0xfaff000, v50
	v_cvt_pk_bf16_f32 v61, v34, v35
	v_cvt_pk_bf16_f32 v60, v32, v33
	v_addc_co_u32_e32 v51, vcc, 0, v51, vcc
	global_store_dwordx2 v[50:51], v[60:61], off offset:2048
	v_cvt_pk_bf16_f32 v61, v38, v39
	v_cvt_pk_bf16_f32 v60, v36, v37
	global_store_dwordx2 v[50:51], v[60:61], off offset:2080
	s_branch .LBB0_345

.LBB0_367:
	v_bfe_u32 v49, v48, 6, 4
	v_cndmask_b32_e64 v49, v50, v49, s[10:11]
	v_cvt_f32_ubyte0_e32 v49, v49
	v_mul_f32_e32 v50, v54, v49
	v_mul_f32_e32 v51, 0.15915494, v50
	v_sin_f32_e32 v50, v51
	v_cos_f32_e32 v60, v51
	v_mul_f32_e32 v51, v55, v49
	v_mul_f32_e32 v61, 0.15915494, v51
	v_mul_f32_e32 v62, v56, v49
	v_mul_f32_e32 v49, v57, v49
	v_sin_f32_e32 v51, v61
	v_mul_f32_e32 v62, 0.15915494, v62
	v_mul_f32_e32 v49, 0.15915494, v49
	v_cos_f32_e32 v61, v61
	v_cos_f32_e32 v65, v62
	v_sin_f32_e32 v67, v62
	v_sin_f32_e32 v69, v49
	v_cos_f32_e32 v68, v49
	v_pk_mul_f32 v[62:63], v[36:37], v[50:51]
	v_pk_mul_f32 v[36:37], v[36:37], v[60:61]
	v_mul_f32_e32 v66, v38, v67
	v_mul_f32_e32 v72, v38, v65
	v_mov_b32_e32 v38, v35
	v_pk_fma_f32 v[60:61], v[32:33], v[60:61], v[62:63] neg_lo:[0,0,1] neg_hi:[0,0,1]
	v_mov_b32_e32 v62, v69
	v_mov_b32_e32 v63, v68
	v_mul_f32_e32 v64, v34, v65
	v_mul_f32_e32 v70, v34, v67
	v_pk_mul_f32 v[34:35], v[38:39], v[68:69]
	v_pk_mul_f32 v[38:39], v[38:39], v[62:63]
	v_mov_b32_e32 v65, v34
	v_mov_b32_e32 v67, v35
	v_mov_b32_e32 v71, v38
	v_mov_b32_e32 v73, v39
	v_pk_add_f32 v[34:35], v[64:65], v[66:67] neg_lo:[0,1] neg_hi:[0,1]
	v_pk_fma_f32 v[36:37], v[32:33], v[50:51], v[36:37]
	v_pk_add_f32 v[38:39], v[70:71], v[72:73]
	v_mov_b32_e32 v32, v60
	v_mov_b32_e32 v33, v61
	s_andn2_b64 vcc, exec, s[22:23]
	s_mov_b64 s[52:53], -1
	s_cbranch_vccz .LBB0_363
.LBB0_368:
	s_and_b64 vcc, exec, s[52:53]
	s_cbranch_vccz .LBB0_345
	v_cvt_pk_bf16_f32 v35, v34, v35
	v_cvt_pk_bf16_f32 v34, v32, v33
	v_mad_i64_i32 v[32:33], s[0:1], v48, s66, v[42:43]
	global_store_dwordx2 v[32:33], v[34:35], off
	v_cvt_pk_bf16_f32 v35, v38, v39
	v_cvt_pk_bf16_f32 v34, v36, v37
	global_store_dwordx2 v[32:33], v[34:35], off offset:32
	s_branch .LBB0_345

.LBB0_373:
	s_waitcnt lgkmcnt(0)
	s_barrier
	ds_write2_b32 v144, v8, v12 offset1:16
	ds_write2_b32 v129, v9, v13 offset0:4 offset1:20
	ds_write2_b32 v132, v10, v14 offset0:8 offset1:24
	ds_write2_b32 v133, v11, v15 offset0:12 offset1:28
	ds_write2_b32 v144, v24, v28 offset0:128 offset1:144
	ds_write2_b32 v129, v25, v29 offset0:132 offset1:148
	ds_write2_b32 v132, v26, v30 offset0:136 offset1:152
	ds_write2_b32 v133, v27, v31 offset0:140 offset1:156
	ds_write2_b32 v120, v0, v4 offset0:64 offset1:80
	ds_write2_b32 v121, v1, v5 offset0:68 offset1:84
	ds_write2_b32 v122, v2, v6 offset0:72 offset1:88
	ds_write2_b32 v123, v3, v7 offset0:76 offset1:92
	ds_write2_b32 v120, v16, v20 offset0:192 offset1:208
	ds_write2_b32 v121, v17, v21 offset0:196 offset1:212
	ds_write2_b32 v122, v18, v22 offset0:200 offset1:216
	ds_write2_b32 v123, v19, v23 offset0:204 offset1:220
	v_mov_b32_e32 v20, v224
	s_waitcnt lgkmcnt(0)
	s_barrier
	v_readlane_b32 s44, v255, 38
	v_lshlrev_b32_e32 v0, 3, v20
	v_and_b32_e32 v1, 0xe0, v0
	v_lshlrev_b32_e32 v0, 2, v20
	v_and_b32_e32 v4, 12, v0
	v_or_b32_e32 v2, v1, v4
	v_or_b32_e32 v0, s16, v2
	v_and_b32_e32 v3, 4, v20
	v_cmp_eq_u32_e64 s[10:11], 0, v3
	v_lshlrev_b32_e32 v2, 2, v2
	v_mov_b32_e32 v3, v131
	v_cmp_eq_u32_e64 s[12:13], 0, v1
	v_ashrrev_i32_e32 v1, 31, v0
	v_lshl_add_u64 v[8:9], s[74:75], 0, v[2:3]
	v_lshlrev_b64 v[2:3], 1, v[0:1]
	v_lshl_add_u64 v[10:11], s[72:73], 0, v[2:3]
	v_lshl_add_u64 v[12:13], s[28:29], 0, v[2:3]
	v_cvt_f32_ubyte0_e32 v2, v4
	v_mul_f32_e32 v2, 0xbf549a78, v2
	v_exp_f32_e32 v22, v2
	v_or_b32_e32 v2, 1, v4
	v_cvt_f32_ubyte0_e32 v2, v2
	v_mul_f32_e32 v2, 0xbf549a78, v2
	v_exp_f32_e32 v23, v2
	v_or_b32_e32 v2, 2, v4
	v_cvt_f32_ubyte0_e32 v2, v2
	v_mul_f32_e32 v2, 0xbf549a78, v2
	v_exp_f32_e32 v24, v2
	v_or_b32_e32 v2, 3, v4
	v_readlane_b32 s50, v255, 44
	v_readlane_b32 s51, v255, 45
	v_cvt_f32_ubyte0_e32 v2, v2
	v_ashrrev_i32_e32 v21, 5, v20
	v_lshl_add_u64 v[14:15], v[0:1], 2, s[50:51]
	v_lshlrev_b32_e32 v0, 5, v20
	v_mul_f32_e32 v2, 0xbf549a78, v2
	v_and_b32_e32 v0, 0x380, v0
	s_or_b32 s17, s38, 0xa0
	v_exp_f32_e32 v25, v2
	v_mad_u64_u32 v[0:1], s[0:1], v21, s60, v[0:1]
	s_cmpk_lt_i32 s38, 0xf60
	v_and_b32_e32 v1, 3, v20
	s_cselect_b64 s[14:15], -1, 0
	s_cmpk_gt_i32 s38, 0xf5f
	v_lshlrev_b32_e32 v1, 4, v1
	s_cselect_b64 s[18:19], -1, 0
	s_mov_b32 s39, 0
	s_and_b64 s[24:25], s[22:23], s[14:15]
	v_add3_u32 v26, v0, v1, 16
	v_lshlrev_b32_e32 v27, 1, v21
	v_readlane_b32 s45, v255, 39
	v_readlane_b32 s46, v255, 40
	v_readlane_b32 s47, v255, 41
	v_readlane_b32 s48, v255, 42
	v_readlane_b32 s49, v255, 43
	v_add_u32_e32 v178, s39, v26
	ds_read_b128 v[170:173], v178
	ds_read_b128 v[174:177], v178 offset:64
	s_branch .LBB0_375

.LBB0_375:
	v_add_u32_e32 v4, s39, v26
	s_waitcnt lgkmcnt(0)
	v_mov_b32_e32 v0, v170
	v_mov_b32_e32 v1, v171
	v_mov_b32_e32 v2, v172
	v_mov_b32_e32 v3, v173
	v_mov_b32_e32 v4, v174
	v_mov_b32_e32 v5, v175
	v_mov_b32_e32 v6, v176
	v_mov_b32_e32 v7, v177
	v_add_u32_e32 v178, s39, v26
	v_add_u32_e32 v178, 0x4100, v178
	ds_read_b128 v[170:173], v178
	ds_read_b128 v[174:177], v178 offset:64
	v_and_b32_e32 v16, 0xffffffc0, v27
	v_and_or_b32 v18, v21, 31, s17
	v_add_u32_e32 v16, v18, v16
	s_and_b64 vcc, exec, s[4:5]
	s_mov_b64 s[0:1], -1
	s_cbranch_vccnz .LBB0_388
	s_and_b64 vcc, exec, s[6:7]
	s_cbranch_vccnz .LBB0_384
	s_andn2_b64 vcc, exec, s[20:21]
	s_cbranch_vccnz .LBB0_381
	s_and_saveexec_b64 s[0:1], s[12:13]
	s_cbranch_execz .LBB0_380
	v_ashrrev_i32_e32 v17, 31, v16
	v_lshlrev_b64 v[28:29], 7, v[16:17]
	v_lshl_add_u64 v[28:29], v[8:9], 0, v[28:29]
	global_store_dwordx4 v[28:29], v[0:3], off
	global_store_dwordx4 v[28:29], v[4:7], off offset:64

.LBB0_381:
	s_andn2_b64 vcc, exec, s[0:1]
	s_cbranch_vccnz .LBB0_383
	v_cvt_pk_bf16_f32 v29, v2, v3
	v_cvt_pk_bf16_f32 v28, v0, v1
	v_mad_i64_i32 v[30:31], s[0:1], v16, s66, v[10:11]
	global_store_dwordx2 v[30:31], v[28:29], off
	v_cvt_pk_bf16_f32 v29, v6, v7
	v_cvt_pk_bf16_f32 v28, v4, v5
	global_store_dwordx2 v[30:31], v[28:29], off offset:32

.LBB0_384:
	s_andn2_b64 vcc, exec, s[0:1]
	s_cbranch_vccnz .LBB0_387
	s_andn2_b64 vcc, exec, s[14:15]
	s_cbranch_vccnz .LBB0_387
	v_ashrrev_i32_e32 v17, 31, v16
	v_lshlrev_b64 v[28:29], 12, v[16:17]
	v_lshl_add_u64 v[28:29], v[14:15], 0, v[28:29]
	v_add_co_u32_e32 v28, vcc, 0x4ffe000, v28
	s_nop 1
	v_addc_co_u32_e32 v29, vcc, 0, v29, vcc
	global_store_dwordx4 v[28:29], v[0:3], off
	global_store_dwordx4 v[28:29], v[4:7], off offset:64

.LBB0_388:
	s_andn2_b64 vcc, exec, s[0:1]
	s_cbranch_vccnz .LBB0_374
	s_andn2_b64 vcc, exec, s[24:25]
	s_cbranch_vccnz .LBB0_395
	v_ashrrev_i32_e32 v17, 31, v16
	v_lshlrev_b64 v[28:29], 12, v[16:17]
	v_lshl_add_u64 v[28:29], v[14:15], 0, v[28:29]
	v_add_co_u32_e32 v28, vcc, 0x3fff000, v28
	s_nop 1
	v_addc_co_u32_e32 v29, vcc, 0, v29, vcc
	global_store_dwordx4 v[28:29], v[0:3], off
	global_store_dwordx4 v[28:29], v[4:7], off offset:64
	v_cndmask_b32_e64 v17, 0, 1, s[18:19]
	v_cmp_ne_u32_e64 s[0:1], 1, v17
	s_andn2_b64 vcc, exec, s[18:19]
	s_cbranch_vccz .LBB0_396

.LBB0_394:
	v_ashrrev_i32_e32 v19, 31, v18
	v_lshlrev_b64 v[18:19], 11, v[18:19]
	v_lshl_add_u64 v[18:19], v[12:13], 0, v[18:19]
	v_add_co_u32_e32 v18, vcc, 0xfaff000, v18
	v_cvt_pk_bf16_f32 v29, v2, v3
	v_cvt_pk_bf16_f32 v28, v0, v1
	v_addc_co_u32_e32 v19, vcc, 0, v19, vcc
	global_store_dwordx2 v[18:19], v[28:29], off offset:2048
	v_cvt_pk_bf16_f32 v29, v6, v7
	v_cvt_pk_bf16_f32 v28, v4, v5
	global_store_dwordx2 v[18:19], v[28:29], off offset:2080
	s_branch .LBB0_374

.LBB0_396:
	v_and_b32_e32 v17, 63, v18
	v_bfe_u32 v18, v16, 6, 4
	v_cndmask_b32_e64 v17, v17, v18, s[10:11]
	v_cvt_f32_ubyte0_e32 v17, v17
	v_mul_f32_e32 v18, v22, v17
	v_mul_f32_e32 v19, 0.15915494, v18
	v_sin_f32_e32 v18, v19
	v_cos_f32_e32 v28, v19
	v_mul_f32_e32 v19, v23, v17
	v_mul_f32_e32 v29, 0.15915494, v19
	v_mul_f32_e32 v30, v24, v17
	v_mul_f32_e32 v17, v25, v17
	v_sin_f32_e32 v19, v29
	v_mul_f32_e32 v30, 0.15915494, v30
	v_mul_f32_e32 v17, 0.15915494, v17
	v_cos_f32_e32 v29, v29
	v_cos_f32_e32 v33, v30
	v_sin_f32_e32 v35, v30
	v_sin_f32_e32 v37, v17
	v_cos_f32_e32 v36, v17
	v_pk_mul_f32 v[30:31], v[4:5], v[18:19]
	v_pk_mul_f32 v[4:5], v[4:5], v[28:29]
	v_mul_f32_e32 v34, v6, v35
	v_mul_f32_e32 v40, v6, v33
	v_mov_b32_e32 v6, v3
	v_pk_fma_f32 v[28:29], v[0:1], v[28:29], v[30:31] neg_lo:[0,0,1] neg_hi:[0,0,1]
	v_mov_b32_e32 v30, v37
	v_mov_b32_e32 v31, v36
	v_mul_f32_e32 v32, v2, v33
	v_mul_f32_e32 v38, v2, v35
	v_pk_mul_f32 v[2:3], v[6:7], v[36:37]
	v_pk_mul_f32 v[6:7], v[6:7], v[30:31]
	v_mov_b32_e32 v33, v2
	v_mov_b32_e32 v35, v3
	v_mov_b32_e32 v39, v6
	v_mov_b32_e32 v41, v7
	v_pk_add_f32 v[2:3], v[32:33], v[34:35] neg_lo:[0,1] neg_hi:[0,1]
	v_pk_fma_f32 v[4:5], v[0:1], v[18:19], v[4:5]
	v_pk_add_f32 v[6:7], v[38:39], v[40:41]
	v_mov_b32_e32 v0, v28
	v_mov_b32_e32 v1, v29
	s_andn2_b64 vcc, exec, s[22:23]
	s_mov_b64 s[26:27], -1
	s_cbranch_vccz .LBB0_392
.LBB0_397:
	s_and_b64 vcc, exec, s[26:27]
	s_cbranch_vccz .LBB0_374
	v_cvt_pk_bf16_f32 v3, v2, v3
	v_cvt_pk_bf16_f32 v2, v0, v1
	v_mad_i64_i32 v[0:1], s[0:1], v16, s66, v[10:11]
	global_store_dwordx2 v[0:1], v[2:3], off
	v_cvt_pk_bf16_f32 v3, v6, v7
	v_cvt_pk_bf16_f32 v2, v4, v5
	global_store_dwordx2 v[0:1], v[2:3], off offset:32
	s_branch .LBB0_374
